# SwiGLU epilogue regenerated: rinv folded into the exp argument and the g*u product (fewer VALU ops per element), rinv LDS reads hoisted
# speedup vs baseline: 1.0139x; 1.0130x over previous
; __device__ __forceinline__ unsigned cvt_pk_bf16(float lo, float hi) { unsigned r; asm volatile("v_cvt_pk_bf16_f32 %0, %1, %2" : "=v"(r) : "v"(lo), "v"(hi)); return r; }
; __device__ __forceinline__ float silu_mul(float g, float u) {
;     const float e = __builtin_amdgcn_exp2f(-1.4426950408889634f * g);
;     return g * __builtin_amdgcn_rcpf(1.0f + e) * u;
; }
;     __device__ __forceinline__ void operator()(const f32x4 (&acc)[2][2][4][2], const Unit& u, int wr, int wc, int fr, int fq) const {
;         const int row0 = u.pm * BM + u.roff + wr * 64 + fr, col0 = u.pn * HALF + wc * 32 + 8 * fq;
; #pragma unroll
;         for (int ai = 0; ai < NAI; ++ai)
; #pragma unroll
;             for (int m = 0; m < 4; ++m) {
;                 const int row = row0 + ai * HALF + m * 16; const float ri = tab[u.par * 256 + ai * HALF + wr * 64 + m * 16 + fr];
;                 const f32x4 g0 = acc[ai][0][m][0] * ri, g1 = acc[ai][0][m][1] * ri, u0 = acc[ai][1][m][0] * ri, u1 = acc[ai][1][m][1] * ri;
;                 u32x4 w;
;                 w.x = pg8::cvt_pk_bf16(silu_mul(g0[0], u0[0]), silu_mul(g0[1], u0[1])); w.y = pg8::cvt_pk_bf16(silu_mul(g0[2], u0[2]), silu_mul(g0[3], u0[3]));
;                 w.z = pg8::cvt_pk_bf16(silu_mul(g1[0], u1[0]), silu_mul(g1[1], u1[1])); w.w = pg8::cvt_pk_bf16(silu_mul(g1[2], u1[2]), silu_mul(g1[3], u1[3]));
;                 *(u32x4*)(O + (size_t)row * DFF + col0) = w;
;                 if (m & 1) asm volatile("" ::: "memory");
;             }
;     }
.LBB0_185:
	v_lshl_add_u32 v147, s55, 10, v145
	ds_read_b32 v202, v147
	ds_read_b32 v203, v147 offset:64
	ds_read_b32 v204, v147 offset:128
	ds_read_b32 v205, v147 offset:192
	ds_read_b32 v206, v147 offset:512
	ds_read_b32 v207, v147 offset:576
	ds_read_b32 v208, v147 offset:640
	ds_read_b32 v209, v147 offset:704
	v_readlane_b32 s18, v254, 11
	v_lshl_or_b32 v140, s56, 7, v144
	v_readlane_b32 s19, v254, 12
	v_lshl_add_u32 v148, s57, 8, v142
	v_ashrrev_i32_e32 v141, 31, v140
	v_lshlrev_b64 v[210:211], 1, v[140:141]
	s_nop 1
	v_mov_b64_e32 v[212:213], s[18:19]
	s_waitcnt lgkmcnt(0)
	v_mul_f32_e32 v214, 0xbfb8aa3b, v202
	v_mul_f32_e32 v220, v202, v202
	v_mul_f32_e32 v216, v126, v214
	v_mul_f32_e32 v217, v127, v214
	v_exp_f32_e32 v216, v216
	v_exp_f32_e32 v217, v217
	v_pk_mul_f32 v[218:219], v[126:127], v[118:119]
	v_pk_add_f32 v[216:217], v[216:217], 1.0 op_sel_hi:[1,0]
	v_pk_mul_f32 v[218:219], v[218:219], v[220:221] op_sel_hi:[1,0]
	v_rcp_f32_e32 v216, v216
	v_rcp_f32_e32 v217, v217
	s_nop 0
	v_pk_mul_f32 v[218:219], v[218:219], v[216:217]
	v_cvt_pk_bf16_f32 v226, v218, v219
	v_mul_f32_e32 v216, v128, v214
	v_mul_f32_e32 v217, v129, v214
	v_exp_f32_e32 v216, v216
	v_exp_f32_e32 v217, v217
	v_pk_mul_f32 v[218:219], v[128:129], v[120:121]
	v_pk_add_f32 v[216:217], v[216:217], 1.0 op_sel_hi:[1,0]
	v_pk_mul_f32 v[218:219], v[218:219], v[220:221] op_sel_hi:[1,0]
	v_rcp_f32_e32 v216, v216
	v_rcp_f32_e32 v217, v217
	s_nop 0
	v_pk_mul_f32 v[218:219], v[218:219], v[216:217]
	v_cvt_pk_bf16_f32 v227, v218, v219
	v_mul_f32_e32 v216, v122, v214
	v_mul_f32_e32 v217, v123, v214
	v_exp_f32_e32 v216, v216
	v_exp_f32_e32 v217, v217
	v_pk_mul_f32 v[218:219], v[122:123], v[114:115]
	v_pk_add_f32 v[216:217], v[216:217], 1.0 op_sel_hi:[1,0]
	v_pk_mul_f32 v[218:219], v[218:219], v[220:221] op_sel_hi:[1,0]
	v_rcp_f32_e32 v216, v216
	v_rcp_f32_e32 v217, v217
	s_nop 0
	v_pk_mul_f32 v[218:219], v[218:219], v[216:217]
	v_cvt_pk_bf16_f32 v228, v218, v219
	v_mul_f32_e32 v216, v124, v214
	v_mul_f32_e32 v217, v125, v214
	v_exp_f32_e32 v216, v216
	v_exp_f32_e32 v217, v217
	v_pk_mul_f32 v[218:219], v[124:125], v[116:117]
	v_pk_add_f32 v[216:217], v[216:217], 1.0 op_sel_hi:[1,0]
	v_pk_mul_f32 v[218:219], v[218:219], v[220:221] op_sel_hi:[1,0]
	v_rcp_f32_e32 v216, v216
	v_rcp_f32_e32 v217, v217
	s_nop 0
	v_pk_mul_f32 v[218:219], v[218:219], v[216:217]
	v_cvt_pk_bf16_f32 v229, v218, v219
	v_mov_b32_e32 v222, v148
	v_mad_i64_i32 v[224:225], s[18:19], v222, s41, v[212:213]
	v_lshl_add_u64 v[224:225], v[224:225], 0, v[210:211]
	global_store_dwordx4 v[224:225], v[226:229], off
	v_mul_f32_e32 v214, 0xbfb8aa3b, v203
	v_mul_f32_e32 v220, v203, v203
	v_mul_f32_e32 v216, v110, v214
	v_mul_f32_e32 v217, v111, v214
	v_exp_f32_e32 v216, v216
	v_exp_f32_e32 v217, v217
	v_pk_mul_f32 v[218:219], v[110:111], v[102:103]
	v_pk_add_f32 v[216:217], v[216:217], 1.0 op_sel_hi:[1,0]
	v_pk_mul_f32 v[218:219], v[218:219], v[220:221] op_sel_hi:[1,0]
	v_rcp_f32_e32 v216, v216
	v_rcp_f32_e32 v217, v217
	s_nop 0
	v_pk_mul_f32 v[218:219], v[218:219], v[216:217]
	v_cvt_pk_bf16_f32 v226, v218, v219
	v_mul_f32_e32 v216, v112, v214
	v_mul_f32_e32 v217, v113, v214
	v_exp_f32_e32 v216, v216
	v_exp_f32_e32 v217, v217
	v_pk_mul_f32 v[218:219], v[112:113], v[104:105]
	v_pk_add_f32 v[216:217], v[216:217], 1.0 op_sel_hi:[1,0]
	v_pk_mul_f32 v[218:219], v[218:219], v[220:221] op_sel_hi:[1,0]
	v_rcp_f32_e32 v216, v216
	v_rcp_f32_e32 v217, v217
	s_nop 0
	v_pk_mul_f32 v[218:219], v[218:219], v[216:217]
	v_cvt_pk_bf16_f32 v227, v218, v219
	v_mul_f32_e32 v216, v106, v214
	v_mul_f32_e32 v217, v107, v214
	v_exp_f32_e32 v216, v216
	v_exp_f32_e32 v217, v217
	v_pk_mul_f32 v[218:219], v[106:107], v[98:99]
	v_pk_add_f32 v[216:217], v[216:217], 1.0 op_sel_hi:[1,0]
	v_pk_mul_f32 v[218:219], v[218:219], v[220:221] op_sel_hi:[1,0]
	v_rcp_f32_e32 v216, v216
	v_rcp_f32_e32 v217, v217
	s_nop 0
	v_pk_mul_f32 v[218:219], v[218:219], v[216:217]
	v_cvt_pk_bf16_f32 v228, v218, v219
	v_mul_f32_e32 v216, v108, v214
	v_mul_f32_e32 v217, v109, v214
	v_exp_f32_e32 v216, v216
	v_exp_f32_e32 v217, v217
	v_pk_mul_f32 v[218:219], v[108:109], v[100:101]
	v_pk_add_f32 v[216:217], v[216:217], 1.0 op_sel_hi:[1,0]
	v_pk_mul_f32 v[218:219], v[218:219], v[220:221] op_sel_hi:[1,0]
	v_rcp_f32_e32 v216, v216
	v_rcp_f32_e32 v217, v217
	s_nop 0
	v_pk_mul_f32 v[218:219], v[218:219], v[216:217]
	v_cvt_pk_bf16_f32 v229, v218, v219
	v_add_u32_e32 v222, 16, v148
	v_mad_i64_i32 v[224:225], s[18:19], v222, s41, v[212:213]
	v_lshl_add_u64 v[224:225], v[224:225], 0, v[210:211]
	global_store_dwordx4 v[224:225], v[226:229], off
	v_mul_f32_e32 v214, 0xbfb8aa3b, v204
	v_mul_f32_e32 v220, v204, v204
	v_mul_f32_e32 v216, v94, v214
	v_mul_f32_e32 v217, v95, v214
	v_exp_f32_e32 v216, v216
	v_exp_f32_e32 v217, v217
	v_pk_mul_f32 v[218:219], v[94:95], v[86:87]
	v_pk_add_f32 v[216:217], v[216:217], 1.0 op_sel_hi:[1,0]
	v_pk_mul_f32 v[218:219], v[218:219], v[220:221] op_sel_hi:[1,0]
	v_rcp_f32_e32 v216, v216
	v_rcp_f32_e32 v217, v217
	s_nop 0
	v_pk_mul_f32 v[218:219], v[218:219], v[216:217]
	v_cvt_pk_bf16_f32 v226, v218, v219
	v_mul_f32_e32 v216, v96, v214
	v_mul_f32_e32 v217, v97, v214
	v_exp_f32_e32 v216, v216
	v_exp_f32_e32 v217, v217
	v_pk_mul_f32 v[218:219], v[96:97], v[88:89]
	v_pk_add_f32 v[216:217], v[216:217], 1.0 op_sel_hi:[1,0]
	v_pk_mul_f32 v[218:219], v[218:219], v[220:221] op_sel_hi:[1,0]
	v_rcp_f32_e32 v216, v216
	v_rcp_f32_e32 v217, v217
	s_nop 0
	v_pk_mul_f32 v[218:219], v[218:219], v[216:217]
	v_cvt_pk_bf16_f32 v227, v218, v219
	v_mul_f32_e32 v216, v90, v214
	v_mul_f32_e32 v217, v91, v214
	v_exp_f32_e32 v216, v216
	v_exp_f32_e32 v217, v217
; __device__ __forceinline__ unsigned cvt_pk_bf16(float lo, float hi) { unsigned r; asm volatile("v_cvt_pk_bf16_f32 %0, %1, %2" : "=v"(r) : "v"(lo), "v"(hi)); return r; }
; __device__ __forceinline__ float silu_mul(float g, float u) {
;     const float e = __builtin_amdgcn_exp2f(-1.4426950408889634f * g);
;     return g * __builtin_amdgcn_rcpf(1.0f + e) * u;
; }
;     __device__ __forceinline__ void operator()(const f32x4 (&acc)[2][2][4][2], const Unit& u, int wr, int wc, int fr, int fq) const {
;         const int row0 = u.pm * BM + u.roff + wr * 64 + fr, col0 = u.pn * HALF + wc * 32 + 8 * fq;
; #pragma unroll
;         for (int ai = 0; ai < NAI; ++ai)
; #pragma unroll
;             for (int m = 0; m < 4; ++m) {
;                 const int row = row0 + ai * HALF + m * 16; const float ri = tab[u.par * 256 + ai * HALF + wr * 64 + m * 16 + fr];
;                 const f32x4 g0 = acc[ai][0][m][0] * ri, g1 = acc[ai][0][m][1] * ri, u0 = acc[ai][1][m][0] * ri, u1 = acc[ai][1][m][1] * ri;
;                 u32x4 w;
;                 w.x = pg8::cvt_pk_bf16(silu_mul(g0[0], u0[0]), silu_mul(g0[1], u0[1])); w.y = pg8::cvt_pk_bf16(silu_mul(g0[2], u0[2]), silu_mul(g0[3], u0[3]));
;                 w.z = pg8::cvt_pk_bf16(silu_mul(g1[0], u1[0]), silu_mul(g1[1], u1[1])); w.w = pg8::cvt_pk_bf16(silu_mul(g1[2], u1[2]), silu_mul(g1[3], u1[3]));
;                 *(u32x4*)(O + (size_t)row * DFF + col0) = w;
;                 if (m & 1) asm volatile("" ::: "memory");
;             }
;     }
	v_pk_mul_f32 v[218:219], v[90:91], v[82:83]
	v_pk_add_f32 v[216:217], v[216:217], 1.0 op_sel_hi:[1,0]
	v_pk_mul_f32 v[218:219], v[218:219], v[220:221] op_sel_hi:[1,0]
	v_rcp_f32_e32 v216, v216
	v_rcp_f32_e32 v217, v217
	s_nop 0
	v_pk_mul_f32 v[218:219], v[218:219], v[216:217]
	v_cvt_pk_bf16_f32 v228, v218, v219
	v_mul_f32_e32 v216, v92, v214
	v_mul_f32_e32 v217, v93, v214
	v_exp_f32_e32 v216, v216
	v_exp_f32_e32 v217, v217
	v_pk_mul_f32 v[218:219], v[92:93], v[84:85]
	v_pk_add_f32 v[216:217], v[216:217], 1.0 op_sel_hi:[1,0]
	v_pk_mul_f32 v[218:219], v[218:219], v[220:221] op_sel_hi:[1,0]
	v_rcp_f32_e32 v216, v216
	v_rcp_f32_e32 v217, v217
	s_nop 0
	v_pk_mul_f32 v[218:219], v[218:219], v[216:217]
	v_cvt_pk_bf16_f32 v229, v218, v219
	v_add_u32_e32 v222, 32, v148
	v_mad_i64_i32 v[224:225], s[18:19], v222, s41, v[212:213]
	v_lshl_add_u64 v[224:225], v[224:225], 0, v[210:211]
	global_store_dwordx4 v[224:225], v[226:229], off
	v_mul_f32_e32 v214, 0xbfb8aa3b, v205
	v_mul_f32_e32 v220, v205, v205
	v_mul_f32_e32 v216, v76, v214
	v_mul_f32_e32 v217, v77, v214
	v_exp_f32_e32 v216, v216
	v_exp_f32_e32 v217, v217
	v_pk_mul_f32 v[218:219], v[76:77], v[68:69]
	v_pk_add_f32 v[216:217], v[216:217], 1.0 op_sel_hi:[1,0]
	v_pk_mul_f32 v[218:219], v[218:219], v[220:221] op_sel_hi:[1,0]
	v_rcp_f32_e32 v216, v216
	v_rcp_f32_e32 v217, v217
	s_nop 0
	v_pk_mul_f32 v[218:219], v[218:219], v[216:217]
	v_cvt_pk_bf16_f32 v226, v218, v219
	v_mul_f32_e32 v216, v78, v214
	v_mul_f32_e32 v217, v79, v214
	v_exp_f32_e32 v216, v216
	v_exp_f32_e32 v217, v217
	v_pk_mul_f32 v[218:219], v[78:79], v[70:71]
	v_pk_add_f32 v[216:217], v[216:217], 1.0 op_sel_hi:[1,0]
	v_pk_mul_f32 v[218:219], v[218:219], v[220:221] op_sel_hi:[1,0]
	v_rcp_f32_e32 v216, v216
	v_rcp_f32_e32 v217, v217
	s_nop 0
	v_pk_mul_f32 v[218:219], v[218:219], v[216:217]
	v_cvt_pk_bf16_f32 v227, v218, v219
	v_mul_f32_e32 v216, v72, v214
	v_mul_f32_e32 v217, v73, v214
	v_exp_f32_e32 v216, v216
	v_exp_f32_e32 v217, v217
	v_pk_mul_f32 v[218:219], v[72:73], v[64:65]
	v_pk_add_f32 v[216:217], v[216:217], 1.0 op_sel_hi:[1,0]
	v_pk_mul_f32 v[218:219], v[218:219], v[220:221] op_sel_hi:[1,0]
	v_rcp_f32_e32 v216, v216
	v_rcp_f32_e32 v217, v217
	s_nop 0
	v_pk_mul_f32 v[218:219], v[218:219], v[216:217]
	v_cvt_pk_bf16_f32 v228, v218, v219
	v_mul_f32_e32 v216, v74, v214
	v_mul_f32_e32 v217, v75, v214
	v_exp_f32_e32 v216, v216
	v_exp_f32_e32 v217, v217
	v_pk_mul_f32 v[218:219], v[74:75], v[66:67]
	v_pk_add_f32 v[216:217], v[216:217], 1.0 op_sel_hi:[1,0]
	v_pk_mul_f32 v[218:219], v[218:219], v[220:221] op_sel_hi:[1,0]
	v_rcp_f32_e32 v216, v216
	v_rcp_f32_e32 v217, v217
	s_nop 0
	v_pk_mul_f32 v[218:219], v[218:219], v[216:217]
	v_cvt_pk_bf16_f32 v229, v218, v219
	v_add_u32_e32 v222, 48, v148
	v_mad_i64_i32 v[224:225], s[18:19], v222, s41, v[212:213]
	v_lshl_add_u64 v[224:225], v[224:225], 0, v[210:211]
	global_store_dwordx4 v[224:225], v[226:229], off
	v_mul_f32_e32 v214, 0xbfb8aa3b, v206
	v_mul_f32_e32 v220, v206, v206
	v_mul_f32_e32 v216, v60, v214
	v_mul_f32_e32 v217, v61, v214
	v_exp_f32_e32 v216, v216
	v_exp_f32_e32 v217, v217
	v_pk_mul_f32 v[218:219], v[60:61], v[52:53]
	v_pk_add_f32 v[216:217], v[216:217], 1.0 op_sel_hi:[1,0]
	v_pk_mul_f32 v[218:219], v[218:219], v[220:221] op_sel_hi:[1,0]
	v_rcp_f32_e32 v216, v216
	v_rcp_f32_e32 v217, v217
	s_nop 0
	v_pk_mul_f32 v[218:219], v[218:219], v[216:217]
	v_cvt_pk_bf16_f32 v226, v218, v219
	v_mul_f32_e32 v216, v62, v214
	v_mul_f32_e32 v217, v63, v214
	v_exp_f32_e32 v216, v216
	v_exp_f32_e32 v217, v217
	v_pk_mul_f32 v[218:219], v[62:63], v[54:55]
	v_pk_add_f32 v[216:217], v[216:217], 1.0 op_sel_hi:[1,0]
	v_pk_mul_f32 v[218:219], v[218:219], v[220:221] op_sel_hi:[1,0]
	v_rcp_f32_e32 v216, v216
	v_rcp_f32_e32 v217, v217
	s_nop 0
	v_pk_mul_f32 v[218:219], v[218:219], v[216:217]
	v_cvt_pk_bf16_f32 v227, v218, v219
	v_mul_f32_e32 v216, v56, v214
	v_mul_f32_e32 v217, v57, v214
	v_exp_f32_e32 v216, v216
	v_exp_f32_e32 v217, v217
	v_pk_mul_f32 v[218:219], v[56:57], v[48:49]
	v_pk_add_f32 v[216:217], v[216:217], 1.0 op_sel_hi:[1,0]
	v_pk_mul_f32 v[218:219], v[218:219], v[220:221] op_sel_hi:[1,0]
	v_rcp_f32_e32 v216, v216
	v_rcp_f32_e32 v217, v217
	s_nop 0
	v_pk_mul_f32 v[218:219], v[218:219], v[216:217]
	v_cvt_pk_bf16_f32 v228, v218, v219
	v_mul_f32_e32 v216, v58, v214
	v_mul_f32_e32 v217, v59, v214
	v_exp_f32_e32 v216, v216
	v_exp_f32_e32 v217, v217
	v_pk_mul_f32 v[218:219], v[58:59], v[50:51]
	v_pk_add_f32 v[216:217], v[216:217], 1.0 op_sel_hi:[1,0]
	v_pk_mul_f32 v[218:219], v[218:219], v[220:221] op_sel_hi:[1,0]
	v_rcp_f32_e32 v216, v216
	v_rcp_f32_e32 v217, v217
	s_nop 0
	v_pk_mul_f32 v[218:219], v[218:219], v[216:217]
	v_cvt_pk_bf16_f32 v229, v218, v219
	v_add_u32_e32 v222, 0x80, v148
	v_mad_i64_i32 v[224:225], s[18:19], v222, s41, v[212:213]
	v_lshl_add_u64 v[224:225], v[224:225], 0, v[210:211]
	global_store_dwordx4 v[224:225], v[226:229], off
	v_mul_f32_e32 v214, 0xbfb8aa3b, v207
	v_mul_f32_e32 v220, v207, v207
	v_mul_f32_e32 v216, v44, v214
	v_mul_f32_e32 v217, v45, v214
	v_exp_f32_e32 v216, v216
	v_exp_f32_e32 v217, v217
	v_pk_mul_f32 v[218:219], v[44:45], v[36:37]
	v_pk_add_f32 v[216:217], v[216:217], 1.0 op_sel_hi:[1,0]
	v_pk_mul_f32 v[218:219], v[218:219], v[220:221] op_sel_hi:[1,0]
	v_rcp_f32_e32 v216, v216
	v_rcp_f32_e32 v217, v217
	s_nop 0
	v_pk_mul_f32 v[218:219], v[218:219], v[216:217]
	v_cvt_pk_bf16_f32 v226, v218, v219
	v_mul_f32_e32 v216, v46, v214
	v_mul_f32_e32 v217, v47, v214
	v_exp_f32_e32 v216, v216
	v_exp_f32_e32 v217, v217
; __device__ __forceinline__ unsigned cvt_pk_bf16(float lo, float hi) { unsigned r; asm volatile("v_cvt_pk_bf16_f32 %0, %1, %2" : "=v"(r) : "v"(lo), "v"(hi)); return r; }
; #define PG8_BAR __builtin_amdgcn_s_barrier()
; template <class Epi, class Sched, bool ALIGN_EPI = false, bool SP2 = false, bool HALFM = false>
; __device__ __forceinline__ void gemm_phase(PG8_LAS unsigned char* lds, const Gemm g, const Sched& S, const Epi& E) {
;     ...
;         if constexpr (!Epi::AFTER_DRAIN) { E(acc, cur, wr, wc, fr, fq); S.done(cur); }
;         if (!has_next) break;
; #pragma unroll
;         for (int a = 0; a < 2; ++a)
; #pragma unroll
;             for (int b = 0; b < 2; ++b)
; #pragma unroll
;                 for (int m = 0; m < 4; ++m)
; #pragma unroll
;                     for (int n = 0; n < 2; ++n) acc[a][b][m][n] = (f32x4){0.f, 0.f, 0.f, 0.f};
;         cur = nxt; cA = nA; cB = nB; ++ui;
;         if constexpr (ALIGN_EPI) { if (wr == 1) PG8_BAR; }
;     __device__ __forceinline__ void operator()(const f32x4 (&acc)[2][2][4][2], const Unit& u, int wr, int wc, int fr, int fq) const {
;         const int row0 = u.pm * BM + u.roff + wr * 64 + fr, col0 = u.pn * HALF + wc * 32 + 8 * fq;
; #pragma unroll
;         for (int ai = 0; ai < NAI; ++ai)
; #pragma unroll
;             for (int m = 0; m < 4; ++m) {
;                 const int row = row0 + ai * HALF + m * 16; const float ri = tab[u.par * 256 + ai * HALF + wr * 64 + m * 16 + fr];
;                 const f32x4 g0 = acc[ai][0][m][0] * ri, g1 = acc[ai][0][m][1] * ri, u0 = acc[ai][1][m][0] * ri, u1 = acc[ai][1][m][1] * ri;
;                 u32x4 w;
;                 w.x = pg8::cvt_pk_bf16(silu_mul(g0[0], u0[0]), silu_mul(g0[1], u0[1])); w.y = pg8::cvt_pk_bf16(silu_mul(g0[2], u0[2]), silu_mul(g0[3], u0[3]));
;                 w.z = pg8::cvt_pk_bf16(silu_mul(g1[0], u1[0]), silu_mul(g1[1], u1[1])); w.w = pg8::cvt_pk_bf16(silu_mul(g1[2], u1[2]), silu_mul(g1[3], u1[3]));
;                 *(u32x4*)(O + (size_t)row * DFF + col0) = w;
;                 if (m & 1) asm volatile("" ::: "memory");
;             }
;     }
	v_pk_mul_f32 v[218:219], v[46:47], v[38:39]
	v_pk_add_f32 v[216:217], v[216:217], 1.0 op_sel_hi:[1,0]
	v_pk_mul_f32 v[218:219], v[218:219], v[220:221] op_sel_hi:[1,0]
	v_rcp_f32_e32 v216, v216
	v_rcp_f32_e32 v217, v217
	s_nop 0
	v_pk_mul_f32 v[218:219], v[218:219], v[216:217]
	v_cvt_pk_bf16_f32 v227, v218, v219
	v_mul_f32_e32 v216, v40, v214
	v_mul_f32_e32 v217, v41, v214
	v_exp_f32_e32 v216, v216
	v_exp_f32_e32 v217, v217
	v_pk_mul_f32 v[218:219], v[40:41], v[32:33]
	v_pk_add_f32 v[216:217], v[216:217], 1.0 op_sel_hi:[1,0]
	v_pk_mul_f32 v[218:219], v[218:219], v[220:221] op_sel_hi:[1,0]
	v_rcp_f32_e32 v216, v216
	v_rcp_f32_e32 v217, v217
	s_nop 0
	v_pk_mul_f32 v[218:219], v[218:219], v[216:217]
	v_cvt_pk_bf16_f32 v228, v218, v219
	v_mul_f32_e32 v216, v42, v214
	v_mul_f32_e32 v217, v43, v214
	v_exp_f32_e32 v216, v216
	v_exp_f32_e32 v217, v217
	v_pk_mul_f32 v[218:219], v[42:43], v[34:35]
	v_pk_add_f32 v[216:217], v[216:217], 1.0 op_sel_hi:[1,0]
	v_pk_mul_f32 v[218:219], v[218:219], v[220:221] op_sel_hi:[1,0]
	v_rcp_f32_e32 v216, v216
	v_rcp_f32_e32 v217, v217
	s_nop 0
	v_pk_mul_f32 v[218:219], v[218:219], v[216:217]
	v_cvt_pk_bf16_f32 v229, v218, v219
	v_add_u32_e32 v222, 0x90, v148
	v_mad_i64_i32 v[224:225], s[18:19], v222, s41, v[212:213]
	v_lshl_add_u64 v[224:225], v[224:225], 0, v[210:211]
	global_store_dwordx4 v[224:225], v[226:229], off
	v_mul_f32_e32 v214, 0xbfb8aa3b, v208
	v_mul_f32_e32 v220, v208, v208
	v_mul_f32_e32 v216, v28, v214
	v_mul_f32_e32 v217, v29, v214
	v_exp_f32_e32 v216, v216
	v_exp_f32_e32 v217, v217
	v_pk_mul_f32 v[218:219], v[28:29], v[20:21]
	v_pk_add_f32 v[216:217], v[216:217], 1.0 op_sel_hi:[1,0]
	v_pk_mul_f32 v[218:219], v[218:219], v[220:221] op_sel_hi:[1,0]
	v_rcp_f32_e32 v216, v216
	v_rcp_f32_e32 v217, v217
	s_nop 0
	v_pk_mul_f32 v[218:219], v[218:219], v[216:217]
	v_cvt_pk_bf16_f32 v226, v218, v219
	v_mul_f32_e32 v216, v30, v214
	v_mul_f32_e32 v217, v31, v214
	v_exp_f32_e32 v216, v216
	v_exp_f32_e32 v217, v217
	v_pk_mul_f32 v[218:219], v[30:31], v[22:23]
	v_pk_add_f32 v[216:217], v[216:217], 1.0 op_sel_hi:[1,0]
	v_pk_mul_f32 v[218:219], v[218:219], v[220:221] op_sel_hi:[1,0]
	v_rcp_f32_e32 v216, v216
	v_rcp_f32_e32 v217, v217
	s_nop 0
	v_pk_mul_f32 v[218:219], v[218:219], v[216:217]
	v_cvt_pk_bf16_f32 v227, v218, v219
	v_mul_f32_e32 v216, v24, v214
	v_mul_f32_e32 v217, v25, v214
	v_exp_f32_e32 v216, v216
	v_exp_f32_e32 v217, v217
	v_pk_mul_f32 v[218:219], v[24:25], v[16:17]
	v_pk_add_f32 v[216:217], v[216:217], 1.0 op_sel_hi:[1,0]
	v_pk_mul_f32 v[218:219], v[218:219], v[220:221] op_sel_hi:[1,0]
	v_rcp_f32_e32 v216, v216
	v_rcp_f32_e32 v217, v217
	s_nop 0
	v_pk_mul_f32 v[218:219], v[218:219], v[216:217]
	v_cvt_pk_bf16_f32 v228, v218, v219
	v_mul_f32_e32 v216, v26, v214
	v_mul_f32_e32 v217, v27, v214
	v_exp_f32_e32 v216, v216
	v_exp_f32_e32 v217, v217
	v_pk_mul_f32 v[218:219], v[26:27], v[18:19]
	v_pk_add_f32 v[216:217], v[216:217], 1.0 op_sel_hi:[1,0]
	v_pk_mul_f32 v[218:219], v[218:219], v[220:221] op_sel_hi:[1,0]
	v_rcp_f32_e32 v216, v216
	v_rcp_f32_e32 v217, v217
	s_nop 0
	v_pk_mul_f32 v[218:219], v[218:219], v[216:217]
	v_cvt_pk_bf16_f32 v229, v218, v219
	v_add_u32_e32 v222, 0xa0, v148
	v_mad_i64_i32 v[224:225], s[18:19], v222, s41, v[212:213]
	v_lshl_add_u64 v[224:225], v[224:225], 0, v[210:211]
	global_store_dwordx4 v[224:225], v[226:229], off
	v_mul_f32_e32 v214, 0xbfb8aa3b, v209
	v_mul_f32_e32 v220, v209, v209
	v_mul_f32_e32 v216, v12, v214
	v_mul_f32_e32 v217, v13, v214
	v_exp_f32_e32 v216, v216
	v_exp_f32_e32 v217, v217
	v_pk_mul_f32 v[218:219], v[12:13], v[4:5]
	v_pk_add_f32 v[216:217], v[216:217], 1.0 op_sel_hi:[1,0]
	v_pk_mul_f32 v[218:219], v[218:219], v[220:221] op_sel_hi:[1,0]
	v_rcp_f32_e32 v216, v216
	v_rcp_f32_e32 v217, v217
	s_nop 0
	v_pk_mul_f32 v[218:219], v[218:219], v[216:217]
	v_cvt_pk_bf16_f32 v226, v218, v219
	v_mul_f32_e32 v216, v14, v214
	v_mul_f32_e32 v217, v15, v214
	v_exp_f32_e32 v216, v216
	v_exp_f32_e32 v217, v217
	v_pk_mul_f32 v[218:219], v[14:15], v[6:7]
	v_pk_add_f32 v[216:217], v[216:217], 1.0 op_sel_hi:[1,0]
	v_pk_mul_f32 v[218:219], v[218:219], v[220:221] op_sel_hi:[1,0]
	v_rcp_f32_e32 v216, v216
	v_rcp_f32_e32 v217, v217
	s_nop 0
	v_pk_mul_f32 v[218:219], v[218:219], v[216:217]
	v_cvt_pk_bf16_f32 v227, v218, v219
	v_mul_f32_e32 v216, v8, v214
	v_mul_f32_e32 v217, v9, v214
	v_exp_f32_e32 v216, v216
	v_exp_f32_e32 v217, v217
	v_pk_mul_f32 v[218:219], v[8:9], v[0:1]
	v_pk_add_f32 v[216:217], v[216:217], 1.0 op_sel_hi:[1,0]
	v_pk_mul_f32 v[218:219], v[218:219], v[220:221] op_sel_hi:[1,0]
	v_rcp_f32_e32 v216, v216
	v_rcp_f32_e32 v217, v217
	s_nop 0
	v_pk_mul_f32 v[218:219], v[218:219], v[216:217]
	v_cvt_pk_bf16_f32 v228, v218, v219
	v_mul_f32_e32 v216, v10, v214
	v_mul_f32_e32 v217, v11, v214
	v_exp_f32_e32 v216, v216
	v_exp_f32_e32 v217, v217
	v_pk_mul_f32 v[218:219], v[10:11], v[2:3]
	v_pk_add_f32 v[216:217], v[216:217], 1.0 op_sel_hi:[1,0]
	v_pk_mul_f32 v[218:219], v[218:219], v[220:221] op_sel_hi:[1,0]
	v_rcp_f32_e32 v216, v216
	v_rcp_f32_e32 v217, v217
	s_nop 0
	v_pk_mul_f32 v[218:219], v[218:219], v[216:217]
	v_cvt_pk_bf16_f32 v229, v218, v219
	v_add_u32_e32 v222, 0xb0, v148
	v_mad_i64_i32 v[224:225], s[18:19], v222, s41, v[212:213]
	v_lshl_add_u64 v[224:225], v[224:225], 0, v[210:211]
	global_store_dwordx4 v[224:225], v[226:229], off
	s_andn2_b64 vcc, exec, s[16:17]
	s_mov_b64 s[18:19], -1
	s_cbranch_vccnz .LBB0_174
	s_andn2_b64 vcc, exec, s[0:1]
	s_cbranch_vccnz .LBB0_173
	s_barrier
	s_branch .LBB0_173
